# v023 + removed 6 compiler-conservative s_waitcnt vmcnt(0) before V^T tr-reads in attention bodies (explicit vmcnt+barrier protocol already protects them)
# speedup vs baseline: 1.0008x; 1.0008x over previous
; #define LAS __attribute__((address_space(3)))
; DI unsigned pk2(float a, float b) { f32x2 v = {a, b}; bf16v2 r = __builtin_convertvector(v, bf16v2); return __builtin_bit_cast(unsigned, r); }
; template <int MODE, class Src>
; DI void attn_item(LAS unsigned char* lds, const Src& src, const bf16_t* Qp  , bf16_t* Op  , int nband, int jj0, float sink_l2, const LAS float* tbl, int qbase, int tid) {
;     ...
;         if (last) asm volatile("s_waitcnt vmcnt(0)" ::: "memory"); else { if (MODE) asm volatile("s_waitcnt vmcnt(8)" ::: "memory"); else asm volatile("s_waitcnt vmcnt(2)" ::: "memory"); }
;         __builtin_amdgcn_s_barrier(); asm volatile("" ::: "memory");
; #pragma unroll
;         for (int kb = 0; kb < 2; ++kb)
; #pragma unroll
;             for (int st = 0; st < 2; ++st) {
;                 u32x4 pp; pp.x = pk2(s[kb][8 * st + 0], s[kb][8 * st + 1]); pp.y = pk2(s[kb][8 * st + 2], s[kb][8 * st + 3]); pp.z = pk2(s[kb][8 * st + 4], s[kb][8 * st + 5]); pp.w = pk2(s[kb][8 * st + 6], s[kb][8 * st + 7]);
;                 const bf16x8 pf = __builtin_bit_cast(bf16x8, pp);
; #pragma unroll
;                 for (int db = 0; db < 4; ++db) {
;                     s16x4 v2[2];
; #pragma unroll
;                     for (int t = 0; t < 2; ++t) {
;                         const int f = (q << 2) | ((2 * t + h) & 3);
;                         v2[t] = __builtin_amdgcn_ds_read_tr16_b64_v4i16((LAS s16x4*)(Vt + 256 * (32 * kb + 16 * st + 8 * t) + 16 * ((4 * db + vlo) ^ f)));
;                     }
;                     const bf16x8 vf = __builtin_shufflevector(v2[0], v2[1], 0, 1, 2, 3, 4, 5, 6, 7);
;                     o[db] = MFMA32(vf, pf, o[db]);
;                 }
;             }
;         asm volatile("s_waitcnt lgkmcnt(0)" ::: "memory"); __builtin_amdgcn_s_barrier(); asm volatile("" ::: "memory");
;         if (!last) ATT_ISSUE(jj + 1, true);
;     DI void get(int jj, int t, bool isV, const bf16_t*& base, int& st) const {
;         if (chunk < 256) { const int cc = chunk - 2 + jj; base = Z + (size_t)cc * 64 * ZLD + (isV ? C_VB : C_KB) + kv * 128; st = ZLD; return; }
;         const int bs = chunk - 256;
;         if (jj < 2) { base = (isV ? VcB : KcB) + (size_t)(bs * 128 + jj * 64) * 256 + kv * 128; st = 256; return; }
;         base = Z + (size_t)chunk * 64 * ZLD + (isV ? C_VB : C_KB) + kv * 128; st = ZLD;
;     }
.LBB0_497:
	s_barrier
	ds_read_b64_tr_b16 v[180:181], v153
	ds_read_b64_tr_b16 v[182:183], v154 offset:2048
	ds_read_b64_tr_b16 v[186:187], v155
	ds_read_b64_tr_b16 v[188:189], v156 offset:2048
	ds_read_b64_tr_b16 v[190:191], v157
	ds_read_b64_tr_b16 v[192:193], v158 offset:2048
	ds_read_b64_tr_b16 v[204:205], v159
	ds_read_b64_tr_b16 v[206:207], v160 offset:2048
	ds_read_b64_tr_b16 v[208:209], v153 offset:4096
	ds_read_b64_tr_b16 v[210:211], v154 offset:6144
	ds_read_b64_tr_b16 v[212:213], v155 offset:4096
	ds_read_b64_tr_b16 v[214:215], v156 offset:6144
	ds_read_b64_tr_b16 v[230:231], v157 offset:4096
	ds_read_b64_tr_b16 v[232:233], v158 offset:6144
	v_cvt_pk_bf16_f32 v86, v145, v162
	v_cvt_pk_bf16_f32 v87, v167, v169
	v_cvt_pk_bf16_f32 v88, v171, v173
	v_cvt_pk_bf16_f32 v89, v175, v177
	v_cvt_pk_bf16_f32 v78, v78, v79
	v_cvt_pk_bf16_f32 v79, v80, v81
	s_waitcnt lgkmcnt(12)
	v_mfma_f32_32x32x16_bf16 v[52:67], v[180:183], v[86:89], v[52:67]
	ds_read_b64_tr_b16 v[234:235], v153 offset:8192
	ds_read_b64_tr_b16 v[236:237], v154 offset:10240
	v_cvt_pk_bf16_f32 v80, v82, v83
	v_cvt_pk_bf16_f32 v81, v84, v85
	v_cvt_pk_bf16_f32 v70, v70, v71
	v_cvt_pk_bf16_f32 v71, v72, v73
	v_cvt_pk_bf16_f32 v72, v74, v75
	v_cvt_pk_bf16_f32 v73, v76, v77
	s_waitcnt lgkmcnt(12)
	v_mfma_f32_32x32x16_bf16 v[36:51], v[186:189], v[86:89], v[36:51]
	ds_read_b64_tr_b16 v[180:181], v155 offset:8192
	ds_read_b64_tr_b16 v[182:183], v156 offset:10240
	s_andn2_b64 vcc, exec, s[48:49]
	s_waitcnt lgkmcnt(12)
	v_mfma_f32_32x32x16_bf16 v[20:35], v[190:193], v[86:89], v[20:35]
	ds_read_b64_tr_b16 v[186:187], v157 offset:8192
	ds_read_b64_tr_b16 v[188:189], v158 offset:10240
	s_waitcnt lgkmcnt(12)
	v_mfma_f32_32x32x16_bf16 v[4:19], v[204:207], v[86:89], v[4:19]
	ds_read_b64_tr_b16 v[190:191], v159 offset:4096
	ds_read_b64_tr_b16 v[192:193], v160 offset:6144
	v_cvt_pk_bf16_f32 v86, v161, v163
	v_cvt_pk_bf16_f32 v87, v168, v170
	v_cvt_pk_bf16_f32 v88, v172, v174
	v_cvt_pk_bf16_f32 v89, v176, v178
	s_nop 0
	s_waitcnt lgkmcnt(12)
	v_mfma_f32_32x32x16_bf16 v[52:67], v[208:211], v[86:89], v[52:67]
	ds_read_b64_tr_b16 v[204:205], v153 offset:12288
	ds_read_b64_tr_b16 v[206:207], v154 offset:14336
	s_waitcnt lgkmcnt(12)
	v_mfma_f32_32x32x16_bf16 v[36:51], v[212:215], v[86:89], v[36:51]
	ds_read_b64_tr_b16 v[208:209], v155 offset:12288
	ds_read_b64_tr_b16 v[210:211], v156 offset:14336
	s_waitcnt lgkmcnt(12)
	v_mfma_f32_32x32x16_bf16 v[20:35], v[230:233], v[86:89], v[20:35]
	ds_read_b64_tr_b16 v[212:213], v159 offset:8192
	ds_read_b64_tr_b16 v[214:215], v160 offset:10240
	s_waitcnt lgkmcnt(12)
	v_mfma_f32_32x32x16_bf16 v[52:67], v[234:237], v[78:81], v[52:67]
	ds_read_b64_tr_b16 v[230:231], v157 offset:12288
	ds_read_b64_tr_b16 v[232:233], v158 offset:14336
	s_waitcnt lgkmcnt(12)
	v_mfma_f32_32x32x16_bf16 v[36:51], v[180:183], v[78:81], v[36:51]
	ds_read_b64_tr_b16 v[234:235], v159 offset:12288
	ds_read_b64_tr_b16 v[236:237], v160 offset:14336
	s_waitcnt lgkmcnt(12)
	v_mfma_f32_32x32x16_bf16 v[20:35], v[186:189], v[78:81], v[20:35]
	s_waitcnt lgkmcnt(10)
	v_mfma_f32_32x32x16_bf16 v[4:19], v[190:193], v[86:89], v[4:19]
	s_waitcnt lgkmcnt(8)
	v_mfma_f32_32x32x16_bf16 v[52:67], v[204:207], v[70:73], v[52:67]
	s_waitcnt lgkmcnt(6)
	v_mfma_f32_32x32x16_bf16 v[36:51], v[208:211], v[70:73], v[36:51]
	s_waitcnt lgkmcnt(4)
	v_mfma_f32_32x32x16_bf16 v[4:19], v[212:215], v[78:81], v[4:19]
	s_waitcnt lgkmcnt(2)
	v_mfma_f32_32x32x16_bf16 v[20:35], v[230:233], v[70:73], v[20:35]
	s_barrier
	s_waitcnt lgkmcnt(0)
	v_mfma_f32_32x32x16_bf16 v[4:19], v[234:237], v[70:73], v[4:19]
	s_cbranch_vccnz .LBB0_476
	s_cmp_lt_i32 s64, 1
	s_cselect_b64 s[42:43], -1, 0
	v_cndmask_b32_e64 v70, 0, 1, s[42:43]
	s_mov_b64 s[48:49], 0x1a00
	s_and_b64 vcc, exec, s[40:41]
	v_cmp_ne_u32_e64 s[42:43], 1, v70
	s_mov_b64 s[52:53], s[46:47]
	s_mov_b64 s[50:51], 0x1a00
	s_cbranch_vccnz .LBB0_501
	s_and_b64 vcc, exec, s[42:43]
	s_mov_b64 s[52:53], s[38:39]
	s_cbranch_vccnz .LBB0_501
	s_ashr_i32 s45, s44, 31
	s_lshl_b64 s[50:51], s[44:45], 9
	s_add_u32 s52, s58, s50
	s_addc_u32 s53, s59, s51
	s_mov_b64 s[50:51], 0x100

; #define LAS __attribute__((address_space(3)))
; DI unsigned pk2(float a, float b) { f32x2 v = {a, b}; bf16v2 r = __builtin_convertvector(v, bf16v2); return __builtin_bit_cast(unsigned, r); }
; #define MFMA32(a, b, cc) __builtin_amdgcn_mfma_f32_32x32x16_bf16((a), (b), (cc), 0, 0, 0)
; DI void attn_quad(LAS unsigned char* lds, const bf16_t* Z, bf16_t* BR, int c0  , int head, const LAS float* tbl, int tid) {
;     ...
;         float ps = 0.f; const float eoff = bc - mrun;
; #pragma unroll
;         for (int kb = 0; kb < 2; ++kb)
; #pragma unroll
;             for (int i = 0; i < 16; ++i) { s[kb][i] = __builtin_amdgcn_exp2f(__builtin_fmaf(s[kb][i], esc, eoff)); ps += s[kb][i]; }
;         ps += __shfl_xor(ps, 32);
;         lrun += ps;
; #pragma unroll
;         for (int kb = 0; kb < 2; ++kb)
; #pragma unroll
;             for (int st = 0; st < 2; ++st) {
;                 u32x4 pp; pp.x = pk2(s[kb][8 * st + 0], s[kb][8 * st + 1]); pp.y = pk2(s[kb][8 * st + 2], s[kb][8 * st + 3]); pp.z = pk2(s[kb][8 * st + 4], s[kb][8 * st + 5]); pp.w = pk2(s[kb][8 * st + 6], s[kb][8 * st + 7]);
;                 const bf16x8 pf = __builtin_bit_cast(bf16x8, pp);
; #pragma unroll
;                 for (int db = 0; db < 4; ++db) {
;                     s16x4 v2[2];
; #pragma unroll
;                     for (int t = 0; t < 2; ++t) {
;                         const int f = (q << 2) | ((2 * t + h) & 3);
;                         v2[t] = __builtin_amdgcn_ds_read_tr16_b64_v4i16((LAS s16x4*)(Vt + 256 * (32 * kb + 16 * st + 8 * t) + 16 * ((4 * db + vlo) ^ f)));
;                     }
;                     const bf16x8 vf = __builtin_shufflevector(v2[0], v2[1], 0, 1, 2, 3, 4, 5, 6, 7);
;                     o[db] = MFMA32(vf, pf, o[db]);
;                 }
;             }
.LBB0_561:
	v_sub_f32_e32 v100, v100, v149
	v_fma_f32 v68, s23, v68, v100
	v_exp_f32_e32 v101, v68
	v_fma_f32 v69, s23, v69, v100
	v_exp_f32_e32 v102, v69
	v_fma_f32 v69, s23, v70, v100
	v_exp_f32_e32 v103, v69
	v_fma_f32 v69, s23, v71, v100
	v_exp_f32_e32 v104, v69
	v_fma_f32 v69, s23, v72, v100
	v_add_f32_e32 v68, 0, v101
	v_exp_f32_e32 v105, v69
	v_fma_f32 v69, s23, v73, v100
	v_add_f32_e32 v68, v102, v68
	v_exp_f32_e32 v106, v69
	v_fma_f32 v69, s23, v74, v100
	v_add_f32_e32 v68, v103, v68
	v_exp_f32_e32 v107, v69
	v_fma_f32 v69, s23, v75, v100
	v_add_f32_e32 v68, v104, v68
	v_exp_f32_e32 v108, v69
	v_fma_f32 v69, s23, v76, v100
	v_add_f32_e32 v68, v105, v68
	v_exp_f32_e32 v109, v69
	v_fma_f32 v69, s23, v77, v100
	v_add_f32_e32 v68, v106, v68
	v_exp_f32_e32 v110, v69
	v_fma_f32 v69, s23, v78, v100
	v_add_f32_e32 v68, v107, v68
	v_exp_f32_e32 v111, v69
	v_fma_f32 v69, s23, v79, v100
	v_add_f32_e32 v68, v108, v68
	v_exp_f32_e32 v112, v69
	v_fma_f32 v69, s23, v80, v100
	v_add_f32_e32 v68, v109, v68
	v_exp_f32_e32 v113, v69
	v_fma_f32 v69, s23, v81, v100
	v_add_f32_e32 v68, v110, v68
	v_exp_f32_e32 v114, v69
	v_fma_f32 v69, s23, v82, v100
	v_add_f32_e32 v68, v111, v68
	v_exp_f32_e32 v82, v69
	v_fma_f32 v69, s23, v83, v100
	v_add_f32_e32 v68, v112, v68
	v_exp_f32_e32 v83, v69
	v_fma_f32 v69, s23, v84, v100
	v_add_f32_e32 v68, v113, v68
	v_exp_f32_e32 v84, v69
	v_fma_f32 v69, s23, v85, v100
	v_add_f32_e32 v68, v114, v68
	v_exp_f32_e32 v85, v69
	v_fma_f32 v69, s23, v86, v100
	v_add_f32_e32 v68, v82, v68
	v_exp_f32_e32 v86, v69
	v_fma_f32 v69, s23, v87, v100
	v_add_f32_e32 v68, v83, v68
	v_exp_f32_e32 v87, v69
	v_fma_f32 v69, s23, v88, v100
	v_add_f32_e32 v68, v84, v68
	v_exp_f32_e32 v88, v69
	v_fma_f32 v69, s23, v89, v100
	v_add_f32_e32 v68, v85, v68
	v_exp_f32_e32 v89, v69
	v_fma_f32 v69, s23, v90, v100
	v_add_f32_e32 v68, v86, v68
	v_exp_f32_e32 v90, v69
	v_fma_f32 v69, s23, v91, v100
	v_add_f32_e32 v68, v87, v68
	v_exp_f32_e32 v91, v69
	v_add_f32_e32 v68, v88, v68
	v_add_f32_e32 v68, v89, v68
	v_add_f32_e32 v68, v90, v68
	v_add_f32_e32 v69, v91, v68
	v_fma_f32 v68, s23, v92, v100
	v_exp_f32_e32 v68, v68
	v_fma_f32 v75, s23, v98, v100
	v_exp_f32_e32 v92, v75
	v_cvt_pk_bf16_f32 v75, v103, v104
	v_add_f32_e32 v70, v68, v69
	v_fma_f32 v69, s23, v93, v100
	v_exp_f32_e32 v69, v69
	v_cvt_pk_bf16_f32 v76, v105, v106
	v_cvt_pk_bf16_f32 v77, v107, v108
	v_add_u32_e32 v98, v141, v174
	v_add_f32_e32 v71, v69, v70
	v_fma_f32 v70, s23, v94, v100
	v_exp_f32_e32 v70, v70
	v_add_u32_e32 v94, v141, v170
	v_cvt_pk_bf16_f32 v68, v68, v69
	v_add_f32_e32 v72, v70, v71
	v_fma_f32 v71, s23, v95, v100
	v_exp_f32_e32 v71, v71
	v_add_u32_e32 v95, v141, v171
	ds_read_b64_tr_b16 v[116:117], v94
	ds_read_b64_tr_b16 v[118:119], v95 offset:2048
	v_add_f32_e32 v73, v71, v72
	v_fma_f32 v72, s23, v96, v100
	v_exp_f32_e32 v72, v72
	v_add_u32_e32 v96, v141, v172
	v_cvt_pk_bf16_f32 v69, v70, v71
	v_add_f32_e32 v74, v72, v73
	v_fma_f32 v73, s23, v97, v100
	v_exp_f32_e32 v73, v73
	v_fmac_f32_e32 v100, s23, v99
	v_exp_f32_e32 v93, v100
	v_add_u32_e32 v97, v141, v173
	ds_read_b64_tr_b16 v[120:121], v96
	ds_read_b64_tr_b16 v[122:123], v97 offset:2048
	v_add_f32_e32 v74, v73, v74
	v_add_f32_e32 v74, v92, v74
	v_add_f32_e32 v74, v93, v74
	ds_bpermute_b32 v2, v2, v74
	s_waitcnt lgkmcnt(0)
	v_add_u32_e32 v99, v141, v175
	ds_read_b64_tr_b16 v[132:133], v98
	ds_read_b64_tr_b16 v[134:135], v99 offset:2048
	v_add_u32_e32 v100, v141, v169
	v_cvt_pk_bf16_f32 v70, v72, v73
	v_cvt_pk_bf16_f32 v71, v92, v93
	v_add_f32_e32 v2, v74, v2
	v_cvt_pk_bf16_f32 v74, v101, v102
	v_add_u32_e32 v101, v141, v176
	ds_read_b64_tr_b16 v[152:153], v100
	ds_read_b64_tr_b16 v[154:155], v101 offset:2048
	ds_read_b64_tr_b16 v[156:157], v94 offset:4096
	ds_read_b64_tr_b16 v[158:159], v95 offset:6144
	ds_read_b64_tr_b16 v[186:187], v96 offset:4096
	ds_read_b64_tr_b16 v[188:189], v97 offset:6144
	ds_read_b64_tr_b16 v[190:191], v98 offset:4096
	ds_read_b64_tr_b16 v[192:193], v99 offset:6144
	v_add_f32_e32 v145, v145, v2
	s_waitcnt lgkmcnt(12)
	v_mfma_f32_32x32x16_bf16 v[52:67], v[116:119], v[74:77], v[52:67]
	ds_read_b64_tr_b16 v[204:205], v100 offset:4096
	ds_read_b64_tr_b16 v[206:207], v101 offset:6144
	s_waitcnt lgkmcnt(12)
	v_mfma_f32_32x32x16_bf16 v[36:51], v[120:123], v[74:77], v[36:51]
	ds_read_b64_tr_b16 v[116:117], v94 offset:8192
	ds_read_b64_tr_b16 v[118:119], v95 offset:10240
	s_waitcnt lgkmcnt(12)
	v_mfma_f32_32x32x16_bf16 v[20:35], v[132:135], v[74:77], v[20:35]
	ds_read_b64_tr_b16 v[120:121], v96 offset:8192
	ds_read_b64_tr_b16 v[122:123], v97 offset:10240
	s_waitcnt lgkmcnt(12)
	v_mfma_f32_32x32x16_bf16 v[4:19], v[152:155], v[74:77], v[4:19]
	ds_read_b64_tr_b16 v[132:133], v98 offset:8192
	ds_read_b64_tr_b16 v[134:135], v99 offset:10240
	v_cvt_pk_bf16_f32 v74, v109, v110
	v_cvt_pk_bf16_f32 v75, v111, v112
	v_cvt_pk_bf16_f32 v76, v113, v114
	v_cvt_pk_bf16_f32 v77, v82, v83
	s_nop 0
	s_waitcnt lgkmcnt(12)
	v_mfma_f32_32x32x16_bf16 v[52:67], v[156:159], v[74:77], v[52:67]
	ds_read_b64_tr_b16 v[152:153], v100 offset:8192
	ds_read_b64_tr_b16 v[154:155], v101 offset:10240
	s_waitcnt lgkmcnt(12)
	v_mfma_f32_32x32x16_bf16 v[36:51], v[186:189], v[74:77], v[36:51]
	ds_read_b64_tr_b16 v[156:157], v94 offset:12288
	ds_read_b64_tr_b16 v[158:159], v95 offset:14336
	s_waitcnt lgkmcnt(12)
	v_mfma_f32_32x32x16_bf16 v[20:35], v[190:193], v[74:77], v[20:35]
	ds_read_b64_tr_b16 v[186:187], v96 offset:12288
	ds_read_b64_tr_b16 v[188:189], v97 offset:14336
	s_waitcnt lgkmcnt(12)
	v_mfma_f32_32x32x16_bf16 v[4:19], v[204:207], v[74:77], v[4:19]
	ds_read_b64_tr_b16 v[190:191], v98 offset:12288
	ds_read_b64_tr_b16 v[192:193], v99 offset:14336
	v_cvt_pk_bf16_f32 v74, v84, v85
	v_cvt_pk_bf16_f32 v75, v86, v87
	v_cvt_pk_bf16_f32 v76, v88, v89
	v_cvt_pk_bf16_f32 v77, v90, v91
	s_nop 0
	s_waitcnt lgkmcnt(12)
	v_mfma_f32_32x32x16_bf16 v[52:67], v[116:119], v[74:77], v[52:67]
	ds_read_b64_tr_b16 v[204:205], v100 offset:12288
	ds_read_b64_tr_b16 v[206:207], v101 offset:14336
	s_waitcnt lgkmcnt(12)
	v_mfma_f32_32x32x16_bf16 v[36:51], v[120:123], v[74:77], v[36:51]
	s_waitcnt lgkmcnt(10)
	v_mfma_f32_32x32x16_bf16 v[20:35], v[132:135], v[74:77], v[20:35]
	s_waitcnt lgkmcnt(8)
	v_mfma_f32_32x32x16_bf16 v[4:19], v[152:155], v[74:77], v[4:19]
	s_waitcnt lgkmcnt(6)
	v_mfma_f32_32x32x16_bf16 v[52:67], v[156:159], v[68:71], v[52:67]
	s_waitcnt lgkmcnt(4)
	v_mfma_f32_32x32x16_bf16 v[36:51], v[186:189], v[68:71], v[36:51]
	s_waitcnt lgkmcnt(2)
	v_mfma_f32_32x32x16_bf16 v[20:35], v[190:193], v[68:71], v[20:35]
	s_waitcnt lgkmcnt(0)
	v_mfma_f32_32x32x16_bf16 v[4:19], v[204:207], v[68:71], v[4:19]

; #define LAS __attribute__((address_space(3)))
; DI unsigned pk2(float a, float b) { f32x2 v = {a, b}; bf16v2 r = __builtin_convertvector(v, bf16v2); return __builtin_bit_cast(unsigned, r); }
; #define MFMA32(a, b, cc) __builtin_amdgcn_mfma_f32_32x32x16_bf16((a), (b), (cc), 0, 0, 0)
; DI void attn_quad(LAS unsigned char* lds, const bf16_t* Z, bf16_t* BR, int c0  , int head, const LAS float* tbl, int tid) {
;     ...
;         float ps = 0.f; const float eoff = bc - mrun;
; #pragma unroll
;         for (int kb = 0; kb < 2; ++kb)
; #pragma unroll
;             for (int i = 0; i < 16; ++i) { s[kb][i] = __builtin_amdgcn_exp2f(__builtin_fmaf(s[kb][i], esc, eoff)); ps += s[kb][i]; }
;         ps += __shfl_xor(ps, 32);
;         lrun += ps;
; #pragma unroll
;         for (int kb = 0; kb < 2; ++kb)
; #pragma unroll
;             for (int st = 0; st < 2; ++st) {
;                 u32x4 pp; pp.x = pk2(s[kb][8 * st + 0], s[kb][8 * st + 1]); pp.y = pk2(s[kb][8 * st + 2], s[kb][8 * st + 3]); pp.z = pk2(s[kb][8 * st + 4], s[kb][8 * st + 5]); pp.w = pk2(s[kb][8 * st + 6], s[kb][8 * st + 7]);
;                 const bf16x8 pf = __builtin_bit_cast(bf16x8, pp);
; #pragma unroll
;                 for (int db = 0; db < 4; ++db) {
;                     s16x4 v2[2];
; #pragma unroll
;                     for (int t = 0; t < 2; ++t) {
;                         const int f = (q << 2) | ((2 * t + h) & 3);
;                         v2[t] = __builtin_amdgcn_ds_read_tr16_b64_v4i16((LAS s16x4*)(Vt + 256 * (32 * kb + 16 * st + 8 * t) + 16 * ((4 * db + vlo) ^ f)));
;                     }
;                     const bf16x8 vf = __builtin_shufflevector(v2[0], v2[1], 0, 1, 2, 3, 4, 5, 6, 7);
;                     o[db] = MFMA32(vf, pf, o[db]);
;                 }
;             }
.LBB0_564:
	v_sub_f32_e32 v137, v137, v149
	v_fma_f32 v68, s48, v68, v137
	v_exp_f32_e32 v154, v68
	v_fma_f32 v69, s48, v69, v137
	v_exp_f32_e32 v155, v69
	v_fma_f32 v69, s48, v70, v137
	v_exp_f32_e32 v156, v69
	v_fma_f32 v69, s48, v71, v137
	v_exp_f32_e32 v157, v69
	v_fma_f32 v69, s48, v72, v137
	v_add_f32_e32 v68, 0, v154
	v_exp_f32_e32 v158, v69
	v_fma_f32 v69, s48, v73, v137
	v_add_f32_e32 v68, v155, v68
	v_exp_f32_e32 v159, v69
	v_fma_f32 v69, s48, v74, v137
	v_add_f32_e32 v68, v156, v68
	v_exp_f32_e32 v74, v69
	v_fma_f32 v69, s48, v75, v137
	v_add_f32_e32 v68, v157, v68
	v_exp_f32_e32 v75, v69
	v_fma_f32 v69, s48, v76, v137
	v_add_f32_e32 v68, v158, v68
	v_exp_f32_e32 v184, v69
	v_fma_f32 v69, s48, v77, v137
	v_add_f32_e32 v68, v159, v68
	v_exp_f32_e32 v77, v69
	v_fma_f32 v69, s48, v78, v137
	v_add_f32_e32 v68, v74, v68
	v_exp_f32_e32 v185, v69
	v_fma_f32 v69, s48, v79, v137
	v_add_f32_e32 v68, v75, v68
	v_exp_f32_e32 v186, v69
	v_fma_f32 v69, s48, v80, v137
	v_add_f32_e32 v68, v184, v68
	v_exp_f32_e32 v187, v69
	v_fma_f32 v69, s48, v81, v137
	v_add_f32_e32 v68, v77, v68
	v_exp_f32_e32 v188, v69
	v_fma_f32 v69, s48, v82, v137
	v_add_f32_e32 v68, v185, v68
	v_exp_f32_e32 v189, v69
	v_fma_f32 v69, s48, v83, v137
	v_add_f32_e32 v68, v186, v68
	v_exp_f32_e32 v190, v69
	v_fma_f32 v69, s48, v84, v137
	v_add_f32_e32 v68, v187, v68
	v_exp_f32_e32 v191, v69
	v_fma_f32 v69, s48, v85, v137
	v_add_f32_e32 v68, v188, v68
	v_exp_f32_e32 v192, v69
	v_fma_f32 v69, s48, v86, v137
	v_add_f32_e32 v68, v189, v68
	v_exp_f32_e32 v86, v69
	v_fma_f32 v69, s48, v87, v137
	v_add_f32_e32 v68, v190, v68
	v_exp_f32_e32 v87, v69
	v_fma_f32 v69, s48, v88, v137
	v_add_f32_e32 v68, v191, v68
	v_exp_f32_e32 v88, v69
	v_fma_f32 v69, s48, v89, v137
	v_add_f32_e32 v68, v192, v68
	v_exp_f32_e32 v89, v69
	v_fma_f32 v69, s48, v90, v137
	v_add_f32_e32 v68, v86, v68
	v_exp_f32_e32 v90, v69
	v_fma_f32 v69, s48, v91, v137
	v_add_f32_e32 v68, v87, v68
	v_exp_f32_e32 v91, v69
	v_add_f32_e32 v68, v88, v68
	v_add_f32_e32 v68, v89, v68
	v_add_f32_e32 v68, v90, v68
	v_add_f32_e32 v69, v91, v68
	v_fma_f32 v68, s48, v92, v137
	v_exp_f32_e32 v68, v68
	v_fma_f32 v78, s48, v98, v137
	v_exp_f32_e32 v92, v78
	v_add3_u32 v153, s47, v183, v179
	v_add_f32_e32 v70, v68, v69
	v_fma_f32 v69, s48, v93, v137
	v_exp_f32_e32 v69, v69
	v_cvt_pk_bf16_f32 v81, v74, v75
	v_add_u32_e32 v74, v153, v170
	v_add_u32_e32 v75, v153, v171
	v_add_f32_e32 v71, v69, v70
	v_fma_f32 v70, s48, v94, v137
	v_exp_f32_e32 v70, v70
	ds_read_b64_tr_b16 v[204:205], v74 offset:16384
	ds_read_b64_tr_b16 v[206:207], v75 offset:18432
	v_cvt_pk_bf16_f32 v79, v156, v157
	v_add_f32_e32 v72, v70, v71
	v_fma_f32 v71, s48, v95, v137
	v_exp_f32_e32 v71, v71
	v_cvt_pk_bf16_f32 v80, v158, v159
	v_add_u32_e32 v94, v153, v172
	v_add_u32_e32 v95, v153, v173
	ds_read_b64_tr_b16 v[208:209], v94 offset:16384
	ds_read_b64_tr_b16 v[210:211], v95 offset:18432
	v_add_f32_e32 v73, v71, v72
	v_fma_f32 v72, s48, v96, v137
	v_exp_f32_e32 v72, v72
	v_add_u32_e32 v96, v153, v174
	v_add_u32_e32 v98, v153, v169
	v_cvt_pk_bf16_f32 v68, v68, v69
	v_add_f32_e32 v76, v72, v73
	v_fma_f32 v73, s48, v97, v137
	v_exp_f32_e32 v73, v73
	v_fmac_f32_e32 v137, s48, v99
	v_exp_f32_e32 v93, v137
	v_add_u32_e32 v97, v153, v175
	ds_read_b64_tr_b16 v[212:213], v96 offset:16384
	ds_read_b64_tr_b16 v[214:215], v97 offset:18432
	v_add_f32_e32 v76, v73, v76
	v_add_f32_e32 v76, v92, v76
	v_add_f32_e32 v76, v93, v76
	ds_bpermute_b32 v78, v152, v76
	s_waitcnt lgkmcnt(0)
	v_add_u32_e32 v99, v153, v176
	ds_read_b64_tr_b16 v[230:231], v98 offset:16384
	ds_read_b64_tr_b16 v[232:233], v99 offset:18432
	ds_read_b64_tr_b16 v[234:235], v74 offset:20480
	ds_read_b64_tr_b16 v[236:237], v75 offset:22528
	ds_read_b64_tr_b16 v[238:239], v94 offset:20480
	ds_read_b64_tr_b16 v[240:241], v95 offset:22528
	ds_read_b64_tr_b16 v[242:243], v96 offset:20480
	ds_read_b64_tr_b16 v[244:245], v97 offset:22528
	v_cvt_pk_bf16_f32 v69, v70, v71
	v_cvt_pk_bf16_f32 v70, v72, v73
	v_cvt_pk_bf16_f32 v71, v92, v93
	v_add_f32_e32 v76, v76, v78
	v_cvt_pk_bf16_f32 v78, v154, v155
	v_add_f32_e32 v145, v145, v76
	s_nop 0
	s_waitcnt lgkmcnt(12)
	v_mfma_f32_32x32x16_bf16 v[52:67], v[204:207], v[78:81], v[52:67]
	ds_read_b64_tr_b16 v[246:247], v98 offset:20480
	ds_read_b64_tr_b16 v[248:249], v99 offset:22528
	s_waitcnt lgkmcnt(12)
	v_mfma_f32_32x32x16_bf16 v[36:51], v[208:211], v[78:81], v[36:51]
	ds_read_b64_tr_b16 v[204:205], v74 offset:24576
	ds_read_b64_tr_b16 v[206:207], v75 offset:26624
	s_waitcnt lgkmcnt(12)
	v_mfma_f32_32x32x16_bf16 v[20:35], v[212:215], v[78:81], v[20:35]
	ds_read_b64_tr_b16 v[208:209], v94 offset:24576
	ds_read_b64_tr_b16 v[210:211], v95 offset:26624
	s_waitcnt lgkmcnt(12)
	v_mfma_f32_32x32x16_bf16 v[4:19], v[230:233], v[78:81], v[4:19]
	ds_read_b64_tr_b16 v[212:213], v96 offset:24576
	ds_read_b64_tr_b16 v[214:215], v97 offset:26624
	v_cvt_pk_bf16_f32 v78, v184, v77
	v_cvt_pk_bf16_f32 v79, v185, v186
	v_cvt_pk_bf16_f32 v80, v187, v188
	v_cvt_pk_bf16_f32 v81, v189, v190
	s_nop 0
	s_waitcnt lgkmcnt(12)
	v_mfma_f32_32x32x16_bf16 v[52:67], v[234:237], v[78:81], v[52:67]
	ds_read_b64_tr_b16 v[230:231], v74 offset:28672
	ds_read_b64_tr_b16 v[232:233], v75 offset:30720
	s_waitcnt lgkmcnt(12)
	v_mfma_f32_32x32x16_bf16 v[36:51], v[238:241], v[78:81], v[36:51]
	ds_read_b64_tr_b16 v[234:235], v94 offset:28672
	ds_read_b64_tr_b16 v[236:237], v95 offset:30720
	s_waitcnt lgkmcnt(12)
	v_mfma_f32_32x32x16_bf16 v[20:35], v[242:245], v[78:81], v[20:35]
	ds_read_b64_tr_b16 v[238:239], v98 offset:24576
	ds_read_b64_tr_b16 v[240:241], v99 offset:26624
	s_waitcnt lgkmcnt(12)
	v_mfma_f32_32x32x16_bf16 v[4:19], v[246:249], v[78:81], v[4:19]
	ds_read_b64_tr_b16 v[242:243], v96 offset:28672
	ds_read_b64_tr_b16 v[244:245], v97 offset:30720
	v_cvt_pk_bf16_f32 v78, v191, v192
	v_cvt_pk_bf16_f32 v79, v86, v87
	v_cvt_pk_bf16_f32 v80, v88, v89
	v_cvt_pk_bf16_f32 v81, v90, v91
	s_nop 0
	s_waitcnt lgkmcnt(12)
	v_mfma_f32_32x32x16_bf16 v[52:67], v[204:207], v[78:81], v[52:67]
	ds_read_b64_tr_b16 v[246:247], v98 offset:28672
	ds_read_b64_tr_b16 v[248:249], v99 offset:30720
	s_waitcnt lgkmcnt(12)
	v_mfma_f32_32x32x16_bf16 v[36:51], v[208:211], v[78:81], v[36:51]
	s_waitcnt lgkmcnt(10)
	v_mfma_f32_32x32x16_bf16 v[20:35], v[212:215], v[78:81], v[20:35]
	s_waitcnt lgkmcnt(8)
	v_mfma_f32_32x32x16_bf16 v[52:67], v[230:233], v[68:71], v[52:67]
	s_waitcnt lgkmcnt(6)
	v_mfma_f32_32x32x16_bf16 v[36:51], v[234:237], v[68:71], v[36:51]
	s_waitcnt lgkmcnt(4)
	v_mfma_f32_32x32x16_bf16 v[4:19], v[238:241], v[78:81], v[4:19]
	s_waitcnt lgkmcnt(2)
	v_mfma_f32_32x32x16_bf16 v[20:35], v[242:245], v[68:71], v[20:35]
	s_waitcnt lgkmcnt(0)
	v_mfma_f32_32x32x16_bf16 v[4:19], v[246:249], v[68:71], v[4:19]

; #define LAS __attribute__((address_space(3)))
; DI unsigned pk2(float a, float b) { f32x2 v = {a, b}; bf16v2 r = __builtin_convertvector(v, bf16v2); return __builtin_bit_cast(unsigned, r); }
; #define MFMA32(a, b, cc) __builtin_amdgcn_mfma_f32_32x32x16_bf16((a), (b), (cc), 0, 0, 0)
; DI void attn_quad(LAS unsigned char* lds, const bf16_t* Z, bf16_t* BR, int c0  , int head, const LAS float* tbl, int tid) {
;     ...
;         float ps = 0.f; const float eoff = bc - mrun;
; #pragma unroll
;         for (int kb = 0; kb < 2; ++kb)
; #pragma unroll
;             for (int i = 0; i < 16; ++i) { s[kb][i] = __builtin_amdgcn_exp2f(__builtin_fmaf(s[kb][i], esc, eoff)); ps += s[kb][i]; }
;         ps += __shfl_xor(ps, 32);
;         lrun += ps;
; #pragma unroll
;         for (int kb = 0; kb < 2; ++kb)
; #pragma unroll
;             for (int st = 0; st < 2; ++st) {
;                 u32x4 pp; pp.x = pk2(s[kb][8 * st + 0], s[kb][8 * st + 1]); pp.y = pk2(s[kb][8 * st + 2], s[kb][8 * st + 3]); pp.z = pk2(s[kb][8 * st + 4], s[kb][8 * st + 5]); pp.w = pk2(s[kb][8 * st + 6], s[kb][8 * st + 7]);
;                 const bf16x8 pf = __builtin_bit_cast(bf16x8, pp);
; #pragma unroll
;                 for (int db = 0; db < 4; ++db) {
;                     s16x4 v2[2];
; #pragma unroll
;                     for (int t = 0; t < 2; ++t) {
;                         const int f = (q << 2) | ((2 * t + h) & 3);
;                         v2[t] = __builtin_amdgcn_ds_read_tr16_b64_v4i16((LAS s16x4*)(Vt + 256 * (32 * kb + 16 * st + 8 * t) + 16 * ((4 * db + vlo) ^ f)));
;                     }
;                     const bf16x8 vf = __builtin_shufflevector(v2[0], v2[1], 0, 1, 2, 3, 4, 5, 6, 7);
;                     o[db] = MFMA32(vf, pf, o[db]);
;                 }
;             }
.LBB0_586:
	v_sub_f32_e32 v207, v207, v149
	v_fma_f32 v68, s26, v68, v207
	v_exp_f32_e32 v209, v68
	v_fma_f32 v69, s26, v69, v207
	v_exp_f32_e32 v210, v69
	v_fma_f32 v69, s26, v70, v207
	v_exp_f32_e32 v211, v69
	v_fma_f32 v69, s26, v71, v207
	v_exp_f32_e32 v212, v69
	v_fma_f32 v69, s26, v72, v207
	v_add_f32_e32 v68, 0, v209
	v_exp_f32_e32 v213, v69
	v_fma_f32 v69, s26, v73, v207
	v_add_f32_e32 v68, v210, v68
	v_exp_f32_e32 v214, v69
	v_fma_f32 v69, s26, v74, v207
	v_add_f32_e32 v68, v211, v68
	v_exp_f32_e32 v74, v69
	v_fma_f32 v69, s26, v75, v207
	v_add_f32_e32 v68, v212, v68
	v_exp_f32_e32 v75, v69
	v_fma_f32 v69, s26, v76, v207
	v_add_f32_e32 v68, v213, v68
	v_exp_f32_e32 v215, v69
	v_fma_f32 v69, s26, v77, v207
	v_add_f32_e32 v68, v214, v68
	v_exp_f32_e32 v77, v69
	v_fma_f32 v69, s26, v78, v207
	v_add_f32_e32 v68, v74, v68
	v_exp_f32_e32 v216, v69
	v_fma_f32 v69, s26, v79, v207
	v_add_f32_e32 v68, v75, v68
	v_exp_f32_e32 v217, v69
	v_fma_f32 v69, s26, v80, v207
	v_add_f32_e32 v68, v215, v68
	v_exp_f32_e32 v230, v69
	v_fma_f32 v69, s26, v81, v207
	v_add_f32_e32 v68, v77, v68
	v_exp_f32_e32 v231, v69
	v_fma_f32 v69, s26, v82, v207
	v_add_f32_e32 v68, v216, v68
	v_exp_f32_e32 v232, v69
	v_fma_f32 v69, s26, v83, v207
	v_add_f32_e32 v68, v217, v68
	v_exp_f32_e32 v233, v69
	v_fma_f32 v69, s26, v84, v207
	v_add_f32_e32 v68, v230, v68
	v_exp_f32_e32 v234, v69
	v_fma_f32 v69, s26, v85, v207
	v_add_f32_e32 v68, v231, v68
	v_exp_f32_e32 v235, v69
	v_fma_f32 v69, s26, v86, v207
	v_add_f32_e32 v68, v232, v68
	v_exp_f32_e32 v86, v69
	v_fma_f32 v69, s26, v87, v207
	v_add_f32_e32 v68, v233, v68
	v_exp_f32_e32 v87, v69
	v_fma_f32 v69, s26, v88, v207
	v_add_f32_e32 v68, v234, v68
	v_exp_f32_e32 v88, v69
	v_fma_f32 v69, s26, v89, v207
	v_add_f32_e32 v68, v235, v68
	v_exp_f32_e32 v89, v69
	v_fma_f32 v69, s26, v90, v207
	v_add_f32_e32 v68, v86, v68
	v_exp_f32_e32 v90, v69
	v_fma_f32 v69, s26, v91, v207
	v_add_f32_e32 v68, v87, v68
	v_exp_f32_e32 v91, v69
	v_add_f32_e32 v68, v88, v68
	v_add_f32_e32 v68, v89, v68
	v_add_f32_e32 v68, v90, v68
	v_add_f32_e32 v69, v91, v68
	v_fma_f32 v68, s26, v92, v207
	v_exp_f32_e32 v68, v68
	v_fma_f32 v78, s26, v98, v207
	v_exp_f32_e32 v92, v78
	v_cvt_pk_bf16_f32 v81, v74, v75
	v_add_f32_e32 v70, v68, v69
	v_fma_f32 v69, s26, v93, v207
	v_exp_f32_e32 v69, v69
	v_add_u32_e32 v74, v143, v170
	v_add_u32_e32 v75, v143, v171
	ds_read_b64_tr_b16 v[236:237], v74
	ds_read_b64_tr_b16 v[238:239], v75 offset:2048
	v_add_f32_e32 v71, v69, v70
	v_fma_f32 v70, s26, v94, v207
	v_exp_f32_e32 v70, v70
	v_cvt_pk_bf16_f32 v79, v211, v212
	v_cvt_pk_bf16_f32 v80, v213, v214
	v_add_u32_e32 v94, v143, v172
	v_add_f32_e32 v72, v70, v71
	v_fma_f32 v71, s26, v95, v207
	v_exp_f32_e32 v71, v71
	v_add_u32_e32 v95, v143, v173
	ds_read_b64_tr_b16 v[240:241], v94
	ds_read_b64_tr_b16 v[242:243], v95 offset:2048
	v_add_u32_e32 v98, v143, v169
	v_cvt_pk_bf16_f32 v68, v68, v69
	v_add_f32_e32 v73, v71, v72
	v_fma_f32 v72, s26, v96, v207
	v_exp_f32_e32 v72, v72
	v_add_u32_e32 v96, v143, v174
	v_cvt_pk_bf16_f32 v69, v70, v71
	v_add_f32_e32 v76, v72, v73
	v_fma_f32 v73, s26, v97, v207
	v_exp_f32_e32 v73, v73
	v_fmac_f32_e32 v207, s26, v99
	v_exp_f32_e32 v93, v207
	v_add_u32_e32 v97, v143, v175
	ds_read_b64_tr_b16 v[244:245], v96
	ds_read_b64_tr_b16 v[246:247], v97 offset:2048
	v_add_f32_e32 v76, v73, v76
	v_add_f32_e32 v76, v92, v76
	v_add_f32_e32 v76, v93, v76
	ds_bpermute_b32 v78, v208, v76
	s_waitcnt lgkmcnt(0)
	v_add_u32_e32 v99, v143, v176
	ds_read_b64_tr_b16 v[248:249], v98
	ds_read_b64_tr_b16 v[250:251], v99 offset:2048
	v_cvt_pk_bf16_f32 v70, v72, v73
	v_cvt_pk_bf16_f32 v71, v92, v93
	v_add_f32_e32 v76, v76, v78
	v_cvt_pk_bf16_f32 v78, v209, v210
	v_add_f32_e32 v145, v145, v76
	s_nop 0
	s_waitcnt lgkmcnt(6)
	v_mfma_f32_32x32x16_bf16 v[52:67], v[236:239], v[78:81], v[52:67]
	ds_read_b64_tr_b16 v[236:237], v74 offset:4096
	ds_read_b64_tr_b16 v[238:239], v75 offset:6144
	s_waitcnt lgkmcnt(6)
	v_mfma_f32_32x32x16_bf16 v[36:51], v[240:243], v[78:81], v[36:51]
	ds_read_b64_tr_b16 v[240:241], v94 offset:4096
	ds_read_b64_tr_b16 v[242:243], v95 offset:6144
	s_waitcnt lgkmcnt(6)
	v_mfma_f32_32x32x16_bf16 v[20:35], v[244:247], v[78:81], v[20:35]
	ds_read_b64_tr_b16 v[244:245], v96 offset:4096
	ds_read_b64_tr_b16 v[246:247], v97 offset:6144
	s_waitcnt lgkmcnt(6)
	v_mfma_f32_32x32x16_bf16 v[4:19], v[248:251], v[78:81], v[4:19]
	ds_read_b64_tr_b16 v[248:249], v98 offset:4096
	ds_read_b64_tr_b16 v[250:251], v99 offset:6144
	v_cvt_pk_bf16_f32 v78, v215, v77
	v_cvt_pk_bf16_f32 v79, v216, v217
	v_cvt_pk_bf16_f32 v80, v230, v231
	v_cvt_pk_bf16_f32 v81, v232, v233
	s_nop 0
	s_waitcnt lgkmcnt(6)
	v_mfma_f32_32x32x16_bf16 v[52:67], v[236:239], v[78:81], v[52:67]
	ds_read_b64_tr_b16 v[236:237], v74 offset:8192
	ds_read_b64_tr_b16 v[238:239], v75 offset:10240
	s_waitcnt lgkmcnt(6)
	v_mfma_f32_32x32x16_bf16 v[36:51], v[240:243], v[78:81], v[36:51]
	ds_read_b64_tr_b16 v[240:241], v94 offset:8192
	ds_read_b64_tr_b16 v[242:243], v95 offset:10240
	s_waitcnt lgkmcnt(6)
	v_mfma_f32_32x32x16_bf16 v[20:35], v[244:247], v[78:81], v[20:35]
	ds_read_b64_tr_b16 v[244:245], v96 offset:8192
	ds_read_b64_tr_b16 v[246:247], v97 offset:10240
	s_waitcnt lgkmcnt(6)
	v_mfma_f32_32x32x16_bf16 v[4:19], v[248:251], v[78:81], v[4:19]
	ds_read_b64_tr_b16 v[248:249], v74 offset:12288
	ds_read_b64_tr_b16 v[250:251], v75 offset:14336
	v_cvt_pk_bf16_f32 v78, v234, v235
	v_cvt_pk_bf16_f32 v79, v86, v87
	v_cvt_pk_bf16_f32 v80, v88, v89
	v_cvt_pk_bf16_f32 v81, v90, v91
	s_nop 0
	s_waitcnt lgkmcnt(6)
	v_mfma_f32_32x32x16_bf16 v[52:67], v[236:239], v[78:81], v[52:67]
	ds_read_b64_tr_b16 v[236:237], v94 offset:12288
	ds_read_b64_tr_b16 v[238:239], v95 offset:14336
	s_waitcnt lgkmcnt(6)
	v_mfma_f32_32x32x16_bf16 v[36:51], v[240:243], v[78:81], v[36:51]
	ds_read_b64_tr_b16 v[240:241], v98 offset:8192
	ds_read_b64_tr_b16 v[242:243], v99 offset:10240
	s_waitcnt lgkmcnt(6)
	v_mfma_f32_32x32x16_bf16 v[20:35], v[244:247], v[78:81], v[20:35]
	ds_read_b64_tr_b16 v[244:245], v96 offset:12288
	ds_read_b64_tr_b16 v[246:247], v97 offset:14336
	s_waitcnt lgkmcnt(6)
	v_mfma_f32_32x32x16_bf16 v[52:67], v[248:251], v[68:71], v[52:67]
	ds_read_b64_tr_b16 v[248:249], v98 offset:12288
	ds_read_b64_tr_b16 v[250:251], v99 offset:14336
	s_waitcnt lgkmcnt(6)
	v_mfma_f32_32x32x16_bf16 v[36:51], v[236:239], v[68:71], v[36:51]
	s_waitcnt lgkmcnt(4)
	v_mfma_f32_32x32x16_bf16 v[4:19], v[240:243], v[78:81], v[4:19]
	s_waitcnt lgkmcnt(2)
	v_mfma_f32_32x32x16_bf16 v[20:35], v[244:247], v[68:71], v[20:35]
	s_waitcnt lgkmcnt(0)
	v_mfma_f32_32x32x16_bf16 v[4:19], v[248:251], v[68:71], v[4:19]

; #define LAS __attribute__((address_space(3)))
; DI unsigned pk2(float a, float b) { f32x2 v = {a, b}; bf16v2 r = __builtin_convertvector(v, bf16v2); return __builtin_bit_cast(unsigned, r); }
; template <int MODE, class Src>
; DI void attn_item(LAS unsigned char* lds, const Src& src, const bf16_t* Qp  , bf16_t* Op  , int nband, int jj0, float sink_l2, const LAS float* tbl, int qbase, int tid) {
;     ...
;         if (last) asm volatile("s_waitcnt vmcnt(0)" ::: "memory"); else { if (MODE) asm volatile("s_waitcnt vmcnt(8)" ::: "memory"); else asm volatile("s_waitcnt vmcnt(2)" ::: "memory"); }
;         __builtin_amdgcn_s_barrier(); asm volatile("" ::: "memory");
; #pragma unroll
;         for (int kb = 0; kb < 2; ++kb)
; #pragma unroll
;             for (int st = 0; st < 2; ++st) {
;                 u32x4 pp; pp.x = pk2(s[kb][8 * st + 0], s[kb][8 * st + 1]); pp.y = pk2(s[kb][8 * st + 2], s[kb][8 * st + 3]); pp.z = pk2(s[kb][8 * st + 4], s[kb][8 * st + 5]); pp.w = pk2(s[kb][8 * st + 6], s[kb][8 * st + 7]);
;                 const bf16x8 pf = __builtin_bit_cast(bf16x8, pp);
; #pragma unroll
;                 for (int db = 0; db < 4; ++db) {
;                     s16x4 v2[2];
; #pragma unroll
;                     for (int t = 0; t < 2; ++t) {
;                         const int f = (q << 2) | ((2 * t + h) & 3);
;                         v2[t] = __builtin_amdgcn_ds_read_tr16_b64_v4i16((LAS s16x4*)(Vt + 256 * (32 * kb + 16 * st + 8 * t) + 16 * ((4 * db + vlo) ^ f)));
;                     }
;                     const bf16x8 vf = __builtin_shufflevector(v2[0], v2[1], 0, 1, 2, 3, 4, 5, 6, 7);
;                     o[db] = MFMA32(vf, pf, o[db]);
;                 }
;             }
;         asm volatile("s_waitcnt lgkmcnt(0)" ::: "memory"); __builtin_amdgcn_s_barrier(); asm volatile("" ::: "memory");
;         if (!last) ATT_ISSUE(jj + 1, true);
;     DI void get(int jj, int t, bool isV, const bf16_t*& base, int& st) const {
;         const int head = head0 + t;
;         if (chunk < 256) { const int cc = chunk - 8 + jj; base = Z + (size_t)cc * 64 * ZLD + (isV ? C_VC : C_KC) + head * 128; st = ZLD; return; }
;         const int bs = chunk - 256;
;         if (jj < 8) { base = (isV ? VcC : KcC) + (size_t)(bs * 512 + jj * 64) * 1024 + head * 128; st = 1024; return; }
;         base = Z + (size_t)chunk * 64 * ZLD + (isV ? C_VC : C_KC) + head * 128; st = ZLD;
;     }
.LBB0_725:
	s_barrier
	v_add_u32_e32 v102, v193, v170
	v_add_u32_e32 v103, v193, v171
	ds_read_b64_tr_b16 v[206:207], v102
	ds_read_b64_tr_b16 v[208:209], v103 offset:2048
	v_cvt_pk_bf16_f32 v94, v153, v155
	v_cvt_pk_bf16_f32 v95, v157, v159
	v_cvt_pk_bf16_f32 v96, v195, v197
	v_cvt_pk_bf16_f32 v97, v204, v205
	v_add_u32_e32 v104, v193, v172
	v_add_u32_e32 v105, v193, v173
	ds_read_b64_tr_b16 v[210:211], v104
	ds_read_b64_tr_b16 v[212:213], v105 offset:2048
	s_waitcnt lgkmcnt(2)
	v_mfma_f32_32x32x16_bf16 v[66:81], v[206:209], v[94:97], v[66:81]
	v_add_u32_e32 v106, v193, v174
	v_add_u32_e32 v107, v193, v175
	ds_read_b64_tr_b16 v[214:215], v106
	ds_read_b64_tr_b16 v[216:217], v107 offset:2048
	ds_read_b64_tr_b16 v[230:231], v102 offset:4096
	ds_read_b64_tr_b16 v[232:233], v103 offset:6144
	ds_read_b64_tr_b16 v[234:235], v104 offset:4096
	ds_read_b64_tr_b16 v[236:237], v105 offset:6144
	ds_read_b64_tr_b16 v[238:239], v106 offset:4096
	ds_read_b64_tr_b16 v[240:241], v107 offset:6144
	ds_read_b64_tr_b16 v[242:243], v102 offset:8192
	ds_read_b64_tr_b16 v[244:245], v103 offset:10240
	ds_read_b64_tr_b16 v[246:247], v104 offset:8192
	ds_read_b64_tr_b16 v[248:249], v105 offset:10240
	v_add_u32_e32 v108, v193, v169
	v_add_u32_e32 v109, v193, v176
	v_cvt_pk_bf16_f32 v87, v87, v88
	s_waitcnt lgkmcnt(12)
	v_mfma_f32_32x32x16_bf16 v[50:65], v[210:213], v[94:97], v[50:65]
	ds_read_b64_tr_b16 v[206:207], v108
	ds_read_b64_tr_b16 v[208:209], v109 offset:2048
	v_cvt_pk_bf16_f32 v88, v89, v90
	v_cvt_pk_bf16_f32 v89, v91, v92
	v_cvt_pk_bf16_f32 v86, v85, v86
	v_cvt_pk_bf16_f32 v15, v15, v16
	v_cvt_pk_bf16_f32 v16, v17, v82
	s_waitcnt lgkmcnt(12)
	v_mfma_f32_32x32x16_bf16 v[34:49], v[214:217], v[94:97], v[34:49]
	ds_read_b64_tr_b16 v[210:211], v106 offset:8192
	ds_read_b64_tr_b16 v[212:213], v107 offset:10240
	v_cvt_pk_bf16_f32 v17, v83, v84
	v_cvt_pk_bf16_f32 v14, v13, v14
	v_cvt_pk_bf16_f32 v7, v7, v8
	v_cvt_pk_bf16_f32 v8, v9, v10
	s_waitcnt lgkmcnt(12)
	v_mfma_f32_32x32x16_bf16 v[66:81], v[230:233], v[86:89], v[66:81]
	ds_read_b64_tr_b16 v[214:215], v108 offset:4096
	ds_read_b64_tr_b16 v[216:217], v109 offset:6144
	v_cvt_pk_bf16_f32 v9, v11, v12
	v_cvt_pk_bf16_f32 v6, v2, v6
	s_andn2_b64 vcc, exec, s[58:59]
	s_waitcnt lgkmcnt(12)
	v_mfma_f32_32x32x16_bf16 v[50:65], v[234:237], v[86:89], v[50:65]
	ds_read_b64_tr_b16 v[230:231], v102 offset:12288
	ds_read_b64_tr_b16 v[232:233], v103 offset:14336
	s_waitcnt lgkmcnt(12)
	v_mfma_f32_32x32x16_bf16 v[34:49], v[238:241], v[86:89], v[34:49]
	ds_read_b64_tr_b16 v[234:235], v104 offset:12288
	ds_read_b64_tr_b16 v[236:237], v105 offset:14336
	s_waitcnt lgkmcnt(12)
	v_mfma_f32_32x32x16_bf16 v[66:81], v[242:245], v[14:17], v[66:81]
	ds_read_b64_tr_b16 v[238:239], v108 offset:8192
	ds_read_b64_tr_b16 v[240:241], v109 offset:10240
	s_waitcnt lgkmcnt(12)
	v_mfma_f32_32x32x16_bf16 v[50:65], v[246:249], v[14:17], v[50:65]
	ds_read_b64_tr_b16 v[242:243], v106 offset:12288
	ds_read_b64_tr_b16 v[244:245], v107 offset:14336
	s_waitcnt lgkmcnt(12)
	v_mfma_f32_32x32x16_bf16 v[18:33], v[206:209], v[94:97], v[18:33]
	ds_read_b64_tr_b16 v[246:247], v108 offset:12288
	ds_read_b64_tr_b16 v[248:249], v109 offset:14336
	s_waitcnt lgkmcnt(12)
	v_mfma_f32_32x32x16_bf16 v[34:49], v[210:213], v[14:17], v[34:49]
	s_waitcnt lgkmcnt(10)
	v_mfma_f32_32x32x16_bf16 v[18:33], v[214:217], v[86:89], v[18:33]
	s_waitcnt lgkmcnt(8)
	v_mfma_f32_32x32x16_bf16 v[66:81], v[230:233], v[6:9], v[66:81]
	s_waitcnt lgkmcnt(6)
	v_mfma_f32_32x32x16_bf16 v[50:65], v[234:237], v[6:9], v[50:65]
	s_waitcnt lgkmcnt(4)
	v_mfma_f32_32x32x16_bf16 v[18:33], v[238:241], v[14:17], v[18:33]
	s_waitcnt lgkmcnt(2)
	v_mfma_f32_32x32x16_bf16 v[34:49], v[242:245], v[6:9], v[34:49]
	s_barrier
	s_waitcnt lgkmcnt(0)
	v_mfma_f32_32x32x16_bf16 v[18:33], v[246:249], v[6:9], v[18:33]
	s_cbranch_vccnz .LBB0_664
	s_cmp_lt_u32 s85, 7
	s_cselect_b64 s[42:43], -1, 0
	v_cndmask_b32_e64 v2, 0, 1, s[42:43]
	s_mov_b64 s[58:59], 0x1a00
	s_and_b64 vcc, exec, s[40:41]
	v_cmp_ne_u32_e64 s[42:43], 1, v2
	s_mov_b64 s[62:63], s[56:57]
	s_mov_b64 s[60:61], 0x1a00
	s_cbranch_vccnz .LBB0_729
	s_and_b64 vcc, exec, s[42:43]
	s_mov_b64 s[62:63], s[8:9]
	s_cbranch_vccnz .LBB0_729
	s_ashr_i32 s55, s54, 31
	s_lshl_b64 s[60:61], s[54:55], 11
	s_add_u32 s62, s79, s60
	s_addc_u32 s63, s80, s61
	s_mov_b64 s[60:61], 0x400

; #define LAS __attribute__((address_space(3)))
; DI unsigned pk2(float a, float b) { f32x2 v = {a, b}; bf16v2 r = __builtin_convertvector(v, bf16v2); return __builtin_bit_cast(unsigned, r); }
; template <int MODE, class Src>
; DI void attn_item(LAS unsigned char* lds, const Src& src, const bf16_t* Qp  , bf16_t* Op  , int nband, int jj0, float sink_l2, const LAS float* tbl, int qbase, int tid) {
;     ...
;         if (last) asm volatile("s_waitcnt vmcnt(0)" ::: "memory"); else { if (MODE) asm volatile("s_waitcnt vmcnt(8)" ::: "memory"); else asm volatile("s_waitcnt vmcnt(2)" ::: "memory"); }
;         __builtin_amdgcn_s_barrier(); asm volatile("" ::: "memory");
; #pragma unroll
;         for (int kb = 0; kb < 2; ++kb)
; #pragma unroll
;             for (int st = 0; st < 2; ++st) {
;                 u32x4 pp; pp.x = pk2(s[kb][8 * st + 0], s[kb][8 * st + 1]); pp.y = pk2(s[kb][8 * st + 2], s[kb][8 * st + 3]); pp.z = pk2(s[kb][8 * st + 4], s[kb][8 * st + 5]); pp.w = pk2(s[kb][8 * st + 6], s[kb][8 * st + 7]);
;                 const bf16x8 pf = __builtin_bit_cast(bf16x8, pp);
; #pragma unroll
;                 for (int db = 0; db < 4; ++db) {
;                     s16x4 v2[2];
; #pragma unroll
;                     for (int t = 0; t < 2; ++t) {
;                         const int f = (q << 2) | ((2 * t + h) & 3);
;                         v2[t] = __builtin_amdgcn_ds_read_tr16_b64_v4i16((LAS s16x4*)(Vt + 256 * (32 * kb + 16 * st + 8 * t) + 16 * ((4 * db + vlo) ^ f)));
;                     }
;                     const bf16x8 vf = __builtin_shufflevector(v2[0], v2[1], 0, 1, 2, 3, 4, 5, 6, 7);
;                     o[db] = MFMA32(vf, pf, o[db]);
;                 }
;             }
;         asm volatile("s_waitcnt lgkmcnt(0)" ::: "memory"); __builtin_amdgcn_s_barrier(); asm volatile("" ::: "memory");
;         if (!last) ATT_ISSUE(jj + 1, true);
;     DI void get(int jj, int t, bool isV, const bf16_t*& base, int& st) const {
;         if (chunk < 256) { const int cc = chunk - 2 + jj; base = Z + (size_t)cc * 64 * ZLD + (isV ? C_VB : C_KB) + kv * 128; st = ZLD; return; }
;         const int bs = chunk - 256;
;         if (jj < 2) { base = (isV ? VcB : KcB) + (size_t)(bs * 128 + jj * 64) * 256 + kv * 128; st = 256; return; }
;         base = Z + (size_t)chunk * 64 * ZLD + (isV ? C_VB : C_KB) + kv * 128; st = ZLD;
;     }
.LBB0_770:
	s_barrier
	v_add_u32_e32 v2, v155, v170
	v_add_u32_e32 v102, v155, v171
	ds_read_b64_tr_b16 v[186:187], v2
	ds_read_b64_tr_b16 v[188:189], v102 offset:2048
	v_cvt_pk_bf16_f32 v94, v159, v177
	v_cvt_pk_bf16_f32 v95, v178, v179
	v_cvt_pk_bf16_f32 v96, v180, v181
	v_cvt_pk_bf16_f32 v97, v182, v183
	v_add_u32_e32 v103, v155, v172
	v_add_u32_e32 v104, v155, v173
	ds_read_b64_tr_b16 v[190:191], v103
	ds_read_b64_tr_b16 v[192:193], v104 offset:2048
	s_waitcnt lgkmcnt(2)
	v_mfma_f32_32x32x16_bf16 v[66:81], v[186:189], v[94:97], v[66:81]
	v_add_u32_e32 v105, v155, v174
	v_add_u32_e32 v106, v155, v175
	ds_read_b64_tr_b16 v[204:205], v105
	ds_read_b64_tr_b16 v[206:207], v106 offset:2048
	ds_read_b64_tr_b16 v[208:209], v2 offset:4096
	ds_read_b64_tr_b16 v[210:211], v102 offset:6144
	ds_read_b64_tr_b16 v[212:213], v103 offset:4096
	ds_read_b64_tr_b16 v[214:215], v104 offset:6144
	ds_read_b64_tr_b16 v[230:231], v105 offset:4096
	ds_read_b64_tr_b16 v[232:233], v106 offset:6144
	ds_read_b64_tr_b16 v[234:235], v2 offset:8192
	ds_read_b64_tr_b16 v[236:237], v102 offset:10240
	ds_read_b64_tr_b16 v[238:239], v103 offset:8192
	ds_read_b64_tr_b16 v[240:241], v104 offset:10240
	v_add_u32_e32 v107, v155, v169
	v_add_u32_e32 v108, v155, v176
	v_cvt_pk_bf16_f32 v86, v86, v87
	s_waitcnt lgkmcnt(12)
	v_mfma_f32_32x32x16_bf16 v[50:65], v[190:193], v[94:97], v[50:65]
	ds_read_b64_tr_b16 v[186:187], v107
	ds_read_b64_tr_b16 v[188:189], v108 offset:2048
	v_cvt_pk_bf16_f32 v87, v88, v89
	v_cvt_pk_bf16_f32 v88, v90, v91
	v_cvt_pk_bf16_f32 v89, v92, v93
	v_cvt_pk_bf16_f32 v14, v14, v15
	v_cvt_pk_bf16_f32 v15, v16, v17
	s_waitcnt lgkmcnt(12)
	v_mfma_f32_32x32x16_bf16 v[34:49], v[204:207], v[94:97], v[34:49]
	ds_read_b64_tr_b16 v[190:191], v105 offset:8192
	ds_read_b64_tr_b16 v[192:193], v106 offset:10240
	v_cvt_pk_bf16_f32 v16, v82, v83
	v_cvt_pk_bf16_f32 v17, v84, v85
	v_cvt_pk_bf16_f32 v6, v6, v7
	v_cvt_pk_bf16_f32 v7, v8, v9
	s_waitcnt lgkmcnt(12)
	v_mfma_f32_32x32x16_bf16 v[66:81], v[208:211], v[86:89], v[66:81]
	ds_read_b64_tr_b16 v[204:205], v107 offset:4096
	ds_read_b64_tr_b16 v[206:207], v108 offset:6144
	v_cvt_pk_bf16_f32 v8, v10, v11
	v_cvt_pk_bf16_f32 v9, v12, v13
	s_andn2_b64 vcc, exec, s[34:35]
	s_waitcnt lgkmcnt(12)
	v_mfma_f32_32x32x16_bf16 v[50:65], v[212:215], v[86:89], v[50:65]
	ds_read_b64_tr_b16 v[208:209], v2 offset:12288
	ds_read_b64_tr_b16 v[210:211], v102 offset:14336
	s_waitcnt lgkmcnt(12)
	v_mfma_f32_32x32x16_bf16 v[34:49], v[230:233], v[86:89], v[34:49]
	ds_read_b64_tr_b16 v[212:213], v103 offset:12288
	ds_read_b64_tr_b16 v[214:215], v104 offset:14336
	s_waitcnt lgkmcnt(12)
	v_mfma_f32_32x32x16_bf16 v[66:81], v[234:237], v[14:17], v[66:81]
	ds_read_b64_tr_b16 v[230:231], v107 offset:8192
	ds_read_b64_tr_b16 v[232:233], v108 offset:10240
	s_waitcnt lgkmcnt(12)
	v_mfma_f32_32x32x16_bf16 v[50:65], v[238:241], v[14:17], v[50:65]
	ds_read_b64_tr_b16 v[234:235], v105 offset:12288
	ds_read_b64_tr_b16 v[236:237], v106 offset:14336
	s_waitcnt lgkmcnt(12)
	v_mfma_f32_32x32x16_bf16 v[18:33], v[186:189], v[94:97], v[18:33]
	ds_read_b64_tr_b16 v[238:239], v107 offset:12288
	ds_read_b64_tr_b16 v[240:241], v108 offset:14336
	s_waitcnt lgkmcnt(12)
	v_mfma_f32_32x32x16_bf16 v[34:49], v[190:193], v[14:17], v[34:49]
	s_waitcnt lgkmcnt(10)
	v_mfma_f32_32x32x16_bf16 v[18:33], v[204:207], v[86:89], v[18:33]
	s_waitcnt lgkmcnt(8)
	v_mfma_f32_32x32x16_bf16 v[66:81], v[208:211], v[6:9], v[66:81]
	s_waitcnt lgkmcnt(6)
	v_mfma_f32_32x32x16_bf16 v[50:65], v[212:215], v[6:9], v[50:65]
	s_waitcnt lgkmcnt(4)
	v_mfma_f32_32x32x16_bf16 v[18:33], v[230:233], v[14:17], v[18:33]
	s_waitcnt lgkmcnt(2)
	v_mfma_f32_32x32x16_bf16 v[34:49], v[234:237], v[6:9], v[34:49]
	s_barrier
	s_waitcnt lgkmcnt(0)
	v_mfma_f32_32x32x16_bf16 v[18:33], v[238:241], v[6:9], v[18:33]
	s_cbranch_vccnz .LBB0_753
	v_readlane_b32 s38, v253, 61
	s_cmp_eq_u32 s18, 0
	v_readlane_b32 s39, v253, 62
	s_mov_b64 s[42:43], -1
	s_cselect_b64 s[34:35], -1, 0
	s_and_b64 vcc, exec, s[38:39]
	s_cbranch_vccz .LBB0_773
	s_and_b64 s[38:39], s[34:35], exec
	s_movk_i32 s12, 0x1a00
	s_cselect_b32 s12, 0x100, s12
	s_cselect_b32 s39, s56, s54
	s_cselect_b32 s38, s55, s53
	s_mov_b64 s[42:43], 0
	s_mov_b64 s[40:41], s[12:13]
